# LRU scan1: issue the 48 first-batch loads together (fresh dest regs), one wait, conversions after
# speedup vs baseline: 1.0025x; 1.0025x over previous
; __device__ __forceinline__ int launder(int v) { asm volatile("" : "+v"(v)); return v; }
; __device__ __forceinline__ float lru_sp(float lam) { const float x = -lam; return -8.0f * ((x > 0.f ? x : 0.f) + log1pf(__expf(-fabsf(x)))); }
; __device__ __forceinline__ void lru_ab(float r, float ii, float xcv, float sp, float& a, float& b) {
;     const float la = r * sp;
;     a = __expf(la);
;     const float em = la > -0.01f ? -2.0f * la * (1.0f + la * (1.0f + 0.6666667f * la)) : 1.0f - a * a;
;     b = __builtin_amdgcn_sqrtf(fmaxf(em, 0.f)) * ii * xcv;
; }
; __device__ __forceinline__ void lru_scan1(const bf16_t* Ab, const bf16_t* Bb, const bf16_t* XC, const float* lam, float* PE, int bid, int G) {
;     const int gtid = bid * NTHR + launder(threadIdx.x), nthreads = G * NTHR;
;     for (int item = gtid; item < LRU_NC * D; item += nthreads) {
;         const int ch = item & (D - 1), c = item >> 11;
;         const float sp = lru_sp(lam[ch]);
;         const bf16_t* ap = Ab + (size_t)c * LRU_CH * D + ch; const bf16_t* bp = Bb + (size_t)c * LRU_CH * D + ch; const bf16_t* xp = XC + (size_t)c * LRU_CH * D + ch;
;         float P = 1.f, hst = 0.f;
;         float ra[LB], rx[LB], xv[LB];
; #pragma unroll
;         for (int i = 0; i < LB; ++i) { ra[i] = bf2f(ap[(size_t)i * D]); rx[i] = bf2f(bp[(size_t)i * D]); xv[i] = bf2f(xp[(size_t)i * D]); }
.LBB0_743:
	v_and_b32_e32 v2, 0x7ff, v1
	v_lshlrev_b32_e32 v3, 2, v2
	s_waitcnt lgkmcnt(0)
	global_load_dword v5, v3, s[4:5]
	s_mov_b32 s0, 0xbfb8aa3b
	v_ashrrev_i32_e32 v4, 11, v1
	v_mov_b32_e32 v3, 0
	v_mov_b32_e32 v16, 1.0
	s_mov_b32 s10, 0
	s_waitcnt vmcnt(0)
	v_max_f32_e64 v6, -v5, -v5
	v_mul_f32_e64 v5, |v5|, s0
	v_exp_f32_e32 v5, v5
	v_max_f32_e32 v8, 0, v6
	s_mov_b32 s0, 0x3f317218
	v_add_f32_e32 v9, 1.0, v5
	v_add_f32_e32 v6, -1.0, v9
	v_sub_f32_e32 v7, v6, v9
	v_add_f32_e32 v7, 1.0, v7
	v_sub_f32_e32 v6, v5, v6
	v_add_f32_e32 v10, v6, v7
	v_frexp_mant_f32_e32 v6, v9
	v_cmp_gt_f32_e32 vcc, s47, v6
	v_cvt_f64_f32_e32 v[6:7], v9
	v_frexp_exp_i32_f64_e32 v6, v[6:7]
	v_subbrev_co_u32_e32 v6, vcc, 0, v6, vcc
	v_sub_u32_e32 v7, 0, v6
	v_ldexp_f32 v9, v9, v7
	v_ldexp_f32 v7, v10, v7
	v_add_f32_e32 v10, -1.0, v9
	v_add_f32_e32 v11, 1.0, v10
	v_sub_f32_e32 v11, v9, v11
	v_add_f32_e32 v11, v7, v11
	v_add_f32_e32 v12, v10, v11
	v_sub_f32_e32 v10, v12, v10
	v_sub_f32_e32 v10, v11, v10
	v_add_f32_e32 v11, 1.0, v9
	v_add_f32_e32 v13, -1.0, v11
	v_sub_f32_e32 v9, v9, v13
	v_add_f32_e32 v7, v7, v9
	v_add_f32_e32 v9, v11, v7
	v_sub_f32_e32 v11, v9, v11
	v_sub_f32_e32 v7, v7, v11
	v_rcp_f32_e32 v11, v9
	v_cvt_f32_i32_e32 v6, v6
	v_mul_f32_e32 v13, v12, v11
	v_mul_f32_e32 v14, v9, v13
	v_fma_f32 v15, v13, v9, -v14
	v_fmac_f32_e32 v15, v13, v7
	v_add_f32_e32 v17, v14, v15
	v_sub_f32_e32 v18, v12, v17
	v_sub_f32_e32 v12, v12, v18
	v_sub_f32_e32 v14, v17, v14
	v_sub_f32_e32 v12, v12, v17
	v_add_f32_e32 v10, v10, v12
	v_sub_f32_e32 v12, v14, v15
	v_add_f32_e32 v10, v12, v10
	v_add_f32_e32 v12, v18, v10
	v_mul_f32_e32 v14, v11, v12
	v_mul_f32_e32 v15, v9, v14
	v_fma_f32 v9, v14, v9, -v15
	v_fmac_f32_e32 v9, v14, v7
	v_sub_f32_e32 v7, v18, v12
	v_add_f32_e32 v7, v10, v7
	v_add_f32_e32 v10, v15, v9
	v_sub_f32_e32 v17, v12, v10
	v_sub_f32_e32 v12, v12, v17
	v_sub_f32_e32 v15, v10, v15
	v_sub_f32_e32 v10, v12, v10
	v_add_f32_e32 v7, v7, v10
	v_sub_f32_e32 v9, v15, v9
	v_add_f32_e32 v7, v9, v7
	v_add_f32_e32 v9, v13, v14
	v_add_f32_e32 v7, v17, v7
	v_sub_f32_e32 v10, v9, v13
	v_mul_f32_e32 v7, v11, v7
	v_sub_f32_e32 v10, v14, v10
	v_add_f32_e32 v7, v10, v7
	v_mul_f32_e32 v13, 0x3f317218, v6
	v_add_f32_e32 v10, v9, v7
	v_fma_f32 v14, v6, s0, -v13
	v_mul_f32_e32 v11, v10, v10
	v_mov_b32_e32 v12, 0x3ecc95a3
	v_fmac_f32_e32 v14, 0xb102e308, v6
	v_sub_f32_e32 v6, v10, v9
	v_fmamk_f32 v12, v11, 0x3e9b6dac, v12
	v_sub_f32_e32 v6, v7, v6
	v_add_f32_e32 v7, v13, v14
	v_fmaak_f32 v12, v11, v12, 0x3f2aaada
	v_sub_f32_e32 v9, v7, v13
	v_ldexp_f32 v13, v10, 1
	v_mul_f32_e32 v10, v10, v11
	v_mul_f32_e32 v10, v10, v12
	v_add_f32_e32 v11, v13, v10
	v_sub_f32_e32 v12, v11, v13
	v_ldexp_f32 v6, v6, 1
	v_sub_f32_e32 v10, v10, v12
	v_add_f32_e32 v6, v6, v10
	v_add_f32_e32 v10, v11, v6
	v_sub_f32_e32 v11, v10, v11
	v_sub_f32_e32 v6, v6, v11
	v_add_f32_e32 v11, v7, v10
	v_sub_f32_e32 v12, v11, v7
	v_sub_f32_e32 v13, v11, v12
	v_sub_f32_e32 v9, v14, v9
	v_sub_f32_e32 v7, v7, v13
	v_sub_f32_e32 v10, v10, v12
	v_add_f32_e32 v7, v10, v7
	v_add_f32_e32 v10, v9, v6
	v_sub_f32_e32 v12, v10, v9
	v_sub_f32_e32 v13, v10, v12
	v_sub_f32_e32 v9, v9, v13
	v_sub_f32_e32 v6, v6, v12
	v_add_f32_e32 v7, v10, v7
	v_add_f32_e32 v6, v6, v9
	v_add_f32_e32 v9, v11, v7
	v_sub_f32_e32 v10, v9, v11
	v_sub_f32_e32 v7, v7, v10
	v_add_f32_e32 v6, v6, v7
	s_mov_b32 s0, 0x7f800000
	v_add_f32_e32 v6, v9, v6
	v_cmp_neq_f32_e32 vcc, s0, v5
	v_mov_b32_e32 v7, 0x7fc00000
	s_mov_b32 s0, 0x33800000
	v_cndmask_b32_e32 v6, v241, v6, vcc
	v_cmp_ngt_f32_e32 vcc, -1.0, v5
	v_lshlrev_b32_e32 v10, 1, v2
	v_mov_b32_e32 v11, v0
	v_cndmask_b32_e32 v6, v7, v6, vcc
	v_cmp_neq_f32_e32 vcc, -1.0, v5
	s_nop 1
	v_cndmask_b32_e32 v6, v180, v6, vcc
	v_cmp_lt_f32_e64 vcc, |v5|, s0
	v_readlane_b32 s0, v254, 15
	v_readlane_b32 s1, v254, 16
	v_cndmask_b32_e32 v5, v6, v5, vcc
	v_add_f32_e32 v43, v8, v5
	v_ashrrev_i32_e32 v5, 31, v4
	v_lshlrev_b64 v[12:13], 19, v[4:5]
	v_lshl_add_u64 v[6:7], s[0:1], 0, v[12:13]
	v_readlane_b32 s0, v254, 19
	v_readlane_b32 s1, v254, 20
	v_lshl_add_u64 v[6:7], v[6:7], 0, v[10:11]
	v_lshl_add_u64 v[8:9], s[66:67], 0, v[12:13]
	v_lshl_add_u64 v[12:13], s[0:1], 0, v[12:13]
	v_lshl_add_u64 v[8:9], v[8:9], 0, v[10:11]
	v_lshl_add_u64 v[10:11], v[12:13], 0, v[10:11]
	v_add_co_u32_e32 v12, vcc, s91, v6
	global_load_ushort v19, v[10:11], off
	s_nop 0
	v_addc_co_u32_e32 v13, vcc, 0, v7, vcc
	global_load_ushort v128, v[12:13], off offset:-4096
	global_load_ushort v129, v[6:7], off
	s_movk_i32 s0, 0x4000
	s_mov_b32 s1, 0xe000
	v_mul_f32_e32 v43, 0xc1000000, v43
	s_nop 0
	s_nop 0
	v_add_co_u32_e32 v14, vcc, s91, v8
	s_nop 0
	s_nop 0
	v_addc_co_u32_e32 v15, vcc, 0, v9, vcc
	v_add_co_u32_e32 v20, vcc, s91, v10
	global_load_ushort v130, v[14:15], off offset:-4096
	global_load_ushort v131, v[8:9], off
	v_addc_co_u32_e32 v21, vcc, 0, v11, vcc
	v_add_co_u32_e32 v26, vcc, s0, v6
	global_load_ushort v23, v[20:21], off offset:-4096
	global_load_ushort v22, v[20:21], off
	v_addc_co_u32_e32 v27, vcc, 0, v7, vcc
	global_load_ushort v132, v[26:27], off offset:-4096
	s_nop 0
	global_load_ushort v133, v[12:13], off
	v_add_co_u32_e32 v28, vcc, s0, v8
	s_nop 0
	s_nop 0
; __device__ __forceinline__ void lru_scan1(const bf16_t* Ab, const bf16_t* Bb, const bf16_t* XC, const float* lam, float* PE, int bid, int G) {
;     ...
;         float ra[LB], rx[LB], xv[LB];
; #pragma unroll
;         for (int i = 0; i < LB; ++i) { ra[i] = bf2f(ap[(size_t)i * D]); rx[i] = bf2f(bp[(size_t)i * D]); xv[i] = bf2f(xp[(size_t)i * D]); }
	v_addc_co_u32_e32 v29, vcc, 0, v9, vcc
	s_nop 0
	s_nop 0
	s_nop 0
	s_nop 0
	s_nop 0
	s_nop 0
	global_load_ushort v134, v[28:29], off offset:-4096
	global_load_ushort v135, v[14:15], off
	s_nop 0
	s_nop 0
	v_add_co_u32_e32 v12, vcc, s0, v10
	s_nop 0
	s_nop 0
	v_addc_co_u32_e32 v13, vcc, 0, v11, vcc
	s_movk_i32 s0, 0x6000
	v_add_co_u32_e32 v14, vcc, s0, v6
	global_load_ushort v25, v[12:13], off offset:-4096
	global_load_ushort v24, v[12:13], off
	v_addc_co_u32_e32 v15, vcc, 0, v7, vcc
	global_load_ushort v136, v[14:15], off offset:-4096
	global_load_ushort v137, v[26:27], off
	s_nop 0
	s_nop 0
	v_add_co_u32_e32 v12, vcc, s0, v8
	s_nop 0
	s_nop 0
	v_addc_co_u32_e32 v13, vcc, 0, v9, vcc
	v_add_co_u32_e32 v36, vcc, s0, v10
	s_mov_b32 s0, 0x8000
	s_nop 0
	v_addc_co_u32_e32 v37, vcc, 0, v11, vcc
	global_load_ushort v138, v[12:13], off offset:-4096
	global_load_ushort v139, v[28:29], off
	s_nop 0
	global_load_ushort v29, v[36:37], off offset:-4096
	global_load_ushort v28, v[36:37], off
	v_add_co_u32_e32 v36, vcc, s0, v6
	s_nop 0
	s_nop 0
	v_addc_co_u32_e32 v37, vcc, 0, v7, vcc
	global_load_ushort v140, v[36:37], off offset:-4096
	s_nop 0
	global_load_ushort v141, v[14:15], off
	v_add_co_u32_e32 v40, vcc, s0, v8
	s_nop 0
	s_nop 0
	v_addc_co_u32_e32 v41, vcc, 0, v9, vcc
	s_nop 0
	s_nop 0
	s_nop 0
	s_nop 0
	global_load_ushort v142, v[40:41], off offset:-4096
	s_nop 0
	global_load_ushort v143, v[12:13], off
	s_nop 0
	s_nop 0
	s_nop 0
	s_nop 0
	v_add_co_u32_e32 v12, vcc, s0, v10
	s_mov_b32 s0, 0xa000
	s_nop 0
	v_addc_co_u32_e32 v13, vcc, 0, v11, vcc
	v_add_co_u32_e32 v44, vcc, s0, v6
	global_load_ushort v38, v[12:13], off offset:-4096
	s_nop 0
	global_load_ushort v13, v[12:13], off
	v_addc_co_u32_e32 v45, vcc, 0, v7, vcc
	global_load_ushort v144, v[44:45], off offset:-4096
	s_nop 0
	global_load_ushort v145, v[36:37], off
	v_add_co_u32_e32 v46, vcc, s0, v8
	s_nop 0
	s_nop 0
	v_addc_co_u32_e32 v47, vcc, 0, v9, vcc
	s_nop 0
	s_nop 0
	global_load_ushort v146, v[46:47], off offset:-4096
	global_load_ushort v147, v[40:41], off
	v_add_co_u32_e32 v48, vcc, s0, v10
	s_mov_b32 s0, 0xc000
	s_nop 0
	v_addc_co_u32_e32 v49, vcc, 0, v11, vcc
	global_load_ushort v40, v[48:49], off offset:-4096
	global_load_ushort v39, v[48:49], off
	v_add_co_u32_e32 v48, vcc, s0, v6
	s_nop 0
	s_nop 0
	v_addc_co_u32_e32 v49, vcc, 0, v7, vcc
	s_nop 0
	global_load_ushort v148, v[48:49], off offset:-4096
	global_load_ushort v149, v[44:45], off
	v_add_co_u32_e32 v50, vcc, s0, v8
	s_nop 0
	s_nop 0
	v_addc_co_u32_e32 v51, vcc, 0, v9, vcc
	s_nop 0
	s_nop 0
	global_load_ushort v150, v[50:51], off offset:-4096
	global_load_ushort v151, v[46:47], off
	v_add_co_u32_e32 v44, vcc, s0, v10
	s_mov_b32 s0, 0xd000
	s_nop 0
	v_addc_co_u32_e32 v45, vcc, 0, v11, vcc
	v_add_co_u32_e32 v62, vcc, s1, v6
	global_load_ushort v46, v[44:45], off offset:-4096
	s_nop 0
	global_load_ushort v44, v[44:45], off
	v_addc_co_u32_e32 v63, vcc, 0, v7, vcc
	s_nop 0
	s_nop 0
	s_nop 0
	global_load_ushort v152, v[62:63], off offset:-4096
	global_load_ushort v153, v[48:49], off
	v_add_co_u32_e32 v48, vcc, s0, v8
	s_mov_b32 s0, 0xf000
	s_nop 0
	v_addc_co_u32_e32 v49, vcc, 0, v9, vcc
	s_nop 0
	s_nop 0
	s_nop 0
	s_nop 0
	global_load_ushort v154, v[48:49], off
	global_load_ushort v155, v[50:51], off
	v_add_co_u32_e32 v50, vcc, s1, v10
	s_nop 0
	s_nop 0
	v_addc_co_u32_e32 v51, vcc, 0, v11, vcc
	global_load_ushort v49, v[50:51], off offset:-4096
	global_load_ushort v48, v[50:51], off
	v_add_co_u32_e32 v50, vcc, s0, v6
	s_nop 0
	s_nop 0
	v_addc_co_u32_e32 v51, vcc, 0, v7, vcc
	global_load_ushort v156, v[50:51], off
	s_nop 0
	global_load_ushort v157, v[62:63], off
	s_nop 0
	s_nop 0
	s_nop 0
	s_nop 0
	v_add_co_u32_e32 v50, vcc, 0xf000, v8
	s_nop 1
	v_addc_co_u32_e32 v51, vcc, 0, v9, vcc
	global_load_ushort v158, v[50:51], off
	v_add_co_u32_e32 v50, vcc, 0xe000, v8
	s_nop 1
	v_addc_co_u32_e32 v51, vcc, 0, v9, vcc
	v_add_co_u32_e32 v64, vcc, 0xf000, v10
	global_load_ushort v159, v[50:51], off
	s_nop 0
	v_addc_co_u32_e32 v65, vcc, 0, v11, vcc
	global_load_ushort v52, v[64:65], off
	s_nop 0
	s_nop 0
	s_nop 0
	s_nop 0
	s_waitcnt vmcnt(0)
	v_lshlrev_b32_e32 v30, 16, v128
	v_lshlrev_b32_e32 v33, 16, v129
	v_lshlrev_b32_e32 v17, 16, v130
	v_lshlrev_b32_e32 v18, 16, v131
	v_lshlrev_b32_e32 v31, 16, v132
	v_lshlrev_b32_e32 v34, 16, v133
	v_lshlrev_b32_e32 v20, 16, v134
	v_lshlrev_b32_e32 v21, 16, v135
	v_lshlrev_b32_e32 v32, 16, v136
	v_lshlrev_b32_e32 v35, 16, v137
	v_lshlrev_b32_e32 v26, 16, v138
	v_lshlrev_b32_e32 v27, 16, v139
	v_lshlrev_b32_e32 v53, 16, v140
	v_lshlrev_b32_e32 v57, 16, v141
	v_lshlrev_b32_e32 v14, 16, v142
	v_lshlrev_b32_e32 v15, 16, v143
	v_lshlrev_b32_e32 v54, 16, v144
	v_lshlrev_b32_e32 v58, 16, v145
	v_lshlrev_b32_e32 v36, 16, v146
	v_lshlrev_b32_e32 v37, 16, v147
	v_lshlrev_b32_e32 v55, 16, v148
	v_lshlrev_b32_e32 v59, 16, v149
	v_lshlrev_b32_e32 v41, 16, v150
	v_lshlrev_b32_e32 v42, 16, v151
	v_lshlrev_b32_e32 v56, 16, v152
	v_lshlrev_b32_e32 v60, 16, v153
	v_lshlrev_b32_e32 v45, 16, v154
	v_lshlrev_b32_e32 v47, 16, v155
	v_lshlrev_b32_e32 v61, 16, v156
	v_lshlrev_b32_e32 v62, 16, v157
	v_lshlrev_b32_e32 v51, 16, v158
	v_lshlrev_b32_e32 v50, 16, v159
